# band-unit rebalancing threshold/stride 38 instead of 43
# baseline (speedup 1.0000x reference)
; #define LAS __attribute__((address_space(3)))
; DEVI int otid() { int t = threadIdx.x; asm volatile("" : "+v"(t)); return t; }
; DEVI void band_phase(LAS unsigned char* lds, const bf16_t* EV, bf16_t* O, const float* relb  ) {
;     ...
;     for (int u = blockIdx.x; u < NB * 8 * 8; u += gridDim.x) {
;         const int qb = 7 - ((u >> 3) & 7), h = u & 7, b = u >> 6;
;         const int tw = qb * 256 + wid * 32, m0 = b * SEQ + tw, cw = tw >> 6;
;         { const int tb = otid(); if (tb < RELSZ) ((LAS float*)(lds + OFF_BIAS))[tb] = relb[h * RELSZ + tb] * 1.4426950408889634f; }
;         const int jlo = (4 * qb - 8) < 0 ? 0 : 4 * qb - 8, jhi = 4 * qb + 3;
;         attn_unit<M_BAND>(lds, EV + (size_t)m0 * EVP + EV_QB + h * HD, EVP, EV + (size_t)(b * SEQ) * EVP + EV_KB + h * HD, EV + (size_t)(b * SEQ) * EVP + EV_VB + h * HD, EVP,
;                           O + (size_t)m0 * DM + 1024 + h * HD, DM, jlo, jhi - jlo + 1, 1, cw - 8, cw, tw);
.LBB11_1275:
	v_mov_b32_e32 v1, v0
	s_and_b64 vcc, exec, s[36:37]
	s_cbranch_vccnz .LBB11_1301
	v_readlane_b32 s1, v252, 16
	s_and_b32 s1, s1, 8
	v_readlane_b32 s12, v249, 17
	s_mulk_i32 s1, 0x300
	v_readlane_b32 s18, v249, 23
	v_ashrrev_i32_e32 v1, 1, v1
	v_readlane_b32 s19, v249, 24
	s_add_u32 s10, s18, s1
	v_and_b32_e32 v1, 0xffffffe0, v1
	s_addc_u32 s11, s19, 0
	v_add_u32_e32 v183, 36, v1
	v_readlane_b32 s1, v255, 8
	s_and_b32 s101, s1, 63
	s_cmp_ge_u32 s101, 38
	s_cbranch_scc1 .LBB11_1301
	s_cmp_le_u32 s101, 25
	s_cselect_b32 s101, 38, 0x100
	v_readlane_b32 s13, v249, 18
	v_readlane_b32 s14, v249, 19
	v_readlane_b32 s15, v249, 20
	v_readlane_b32 s16, v249, 21
	v_readlane_b32 s17, v249, 22
	v_readlane_b32 s20, v249, 25
	v_readlane_b32 s21, v249, 26
	v_readlane_b32 s22, v249, 27
	v_readlane_b32 s23, v249, 28
	v_readlane_b32 s24, v249, 29
	v_readlane_b32 s25, v249, 30
	v_readlane_b32 s26, v249, 31
	v_readlane_b32 s27, v249, 32
	s_branch .LBB11_1278
